# attention loop stagger only (waves 4-7 half tile behind)
# baseline (speedup 1.0000x reference)
; DI void attn_unit(LAS unsigned char* lds, const Args& a, int bg, int qt) {
;     ...
;         const float gi = GT[0] * inv;
; #pragma unroll
;         for (int r = 0; r < 16; ++r) { oacc[0][r] += gi * o[0][r]; oacc[1][r] += gi * o[1][r]; o[0][r] = 0.f; o[1][r] = 0.f; }
;         const float f0 = fast_exp2(mu0 - m_ref) * inv;
;         if (two_cmp && hi == 0) { LAS float* sc = (LAS float*)(lds + LDS_SCL) + (hl * 64 + qloc) * 3; sc[0] = f0; sc[1] = inv; sc[2] = xcross * f0; }
;         m_ref = 0.f; l_run = 0.f;
;     }
;     __syncthreads();
;     const unsigned causal_all = (qt == 31) ? 0xffffffffu : ((1u << (qt + 1)) - 1u);
;     if (two_cmp) {
;         const int j = tid & 31;
;         LAS const float* SCL = (LAS const float*)(lds + LDS_SCL);
; #pragma unroll
;         for (int it = 0; it < 4; ++it) { const int q = (tid >> 5) + 16 * it;
;             float v = 0.f;
; #pragma unroll
;             for (int h = 0; h < 4; ++h) { const int hq = h * 64 + q; const float sc = SCL[hq * 3 + (j >> 4)]; v += IMP[hq * IMP_PITCH + j] * sc + ((j == 16) ? SCL[hq * 3 + 2] : 0.f); }
;             const bool forced = (j == 0) || (j == qt) || (j == qt - 1);
;             v = forced ? 1e4f : (j > qt ? -1.0f : v);
;             VAL[q * 32 + j] = v; }
;         __syncthreads();
;         const unsigned causal_bits = (qt == 31) ? 0xffffffffu : ((1u << (qt + 1)) - 1u);
; #pragma unroll
;         for (int it = 0; it < 4; ++it) { const int q = (tid >> 5) + 16 * it;
;             const float v = VAL[q * 32 + j]; int cnt = 0;
; #pragma unroll 8
;             for (int jj = 0; jj < 32; ++jj) { const float ov = VAL[q * 32 + jj]; cnt += ((ov > v) || (ov == v && jj < j)) ? 1 : 0; }
;             const unsigned long long bal = __ballot(cnt < 16);
;             const unsigned mk = ((lane < 32) ? (unsigned)bal : (unsigned)(bal >> 32)) & causal_bits;
;             if ((lane & 31) == 0) MSK[q] = mk; }
;         __syncthreads();
;         if (w == 0) {
;             int ln = lane; asm volatile("" : "+v"(ln));
;             unsigned U = MSK[ln];
; #pragma unroll
;             for (int of = 1; of < 64; of <<= 1) U |= (unsigned)__shfl_xor((int)U, of);
;             const int n = __popc(U), j0 = qt - 8 < 0 ? 0 : qt - 8;
;             if (ln < 32) { if ((U >> ln) & 1u) LIST[__popc(U & ((1u << ln) - 1u))] = ln; }
;             else if (j0 + (ln - 32) <= qt) LIST[n + ln - 32] = j0 + (ln - 32);
.LBB0_776:
	v_pk_fma_f32 v[168:169], v[16:17], v[34:35], 0 op_sel_hi:[1,0,0]
	v_pk_fma_f32 v[170:171], v[14:15], v[34:35], 0 op_sel_hi:[1,0,0]
	v_pk_fma_f32 v[172:173], v[12:13], v[34:35], 0 op_sel_hi:[1,0,0]
	v_pk_fma_f32 v[174:175], v[10:11], v[34:35], 0 op_sel_hi:[1,0,0]
	v_pk_fma_f32 v[176:177], v[8:9], v[34:35], 0 op_sel_hi:[1,0,0]
	v_pk_fma_f32 v[178:179], v[6:7], v[34:35], 0 op_sel_hi:[1,0,0]
	v_pk_fma_f32 v[180:181], v[4:5], v[34:35], 0 op_sel_hi:[1,0,0]
	s_andn2_b64 vcc, exec, s[8:9]
	v_pk_fma_f32 v[182:183], v[2:3], v[34:35], 0 op_sel_hi:[1,0,0]
	s_cbranch_vccnz .LBB0_737
	v_readfirstlane_b32 s98, v184
	s_cmp_lt_u32 s98, 0x100
	s_cbranch_scc1 .Lattn_skip_xp
	s_barrier
.Lattn_skip_xp:
	v_mov_b32_e32 v141, 0
	s_add_i32 s20, s73, -8
	s_sub_i32 s21, 0, s18
	s_sub_i32 s28, 0, s19
	s_movk_i32 s29, 0x4000
	s_mov_b32 s77, 3
	s_mov_b32 s78, s71
	v_mov_b32_e32 v143, 0
	v_mov_b32_e32 v34, 0
	v_mov_b32_e32 v35, v141
	v_mov_b32_e32 v36, 0
	v_mov_b32_e32 v37, v141
	v_mov_b32_e32 v38, 0
	v_mov_b32_e32 v39, v141
	v_mov_b32_e32 v40, 0
	v_mov_b32_e32 v41, v141
	v_mov_b32_e32 v42, 0
	v_mov_b32_e32 v43, v141
	v_mov_b32_e32 v44, 0
	v_mov_b32_e32 v45, v141
	v_mov_b32_e32 v46, 0
	v_mov_b32_e32 v47, v141
	v_mov_b32_e32 v48, 0
	v_mov_b32_e32 v49, v141
	v_mov_b32_e32 v50, 0
	v_mov_b32_e32 v18, 0
	v_mov_b32_e32 v19, v141
	v_mov_b32_e32 v20, v141
	v_mov_b32_e32 v21, v141
	v_mov_b32_e32 v22, v141
	v_mov_b32_e32 v23, v141
	v_mov_b32_e32 v24, v141
	v_mov_b32_e32 v25, v141
	v_mov_b32_e32 v26, v141
	v_mov_b32_e32 v27, v141
	v_mov_b32_e32 v28, v141
	v_mov_b32_e32 v29, v141
	v_mov_b32_e32 v30, v141
	v_mov_b32_e32 v31, v141
	v_mov_b32_e32 v32, v141
	v_mov_b32_e32 v33, v141
	v_mov_b32_e32 v2, v141
	v_mov_b32_e32 v3, v141
	v_mov_b32_e32 v4, v141
	v_mov_b32_e32 v5, v141
	v_mov_b32_e32 v6, v141
	v_mov_b32_e32 v7, v141
	v_mov_b32_e32 v8, v141
	v_mov_b32_e32 v9, v141
	v_mov_b32_e32 v10, v141
	v_mov_b32_e32 v11, v141
	v_mov_b32_e32 v12, v141
	v_mov_b32_e32 v13, v141
	v_mov_b32_e32 v14, v141
	v_mov_b32_e32 v15, v141
	v_mov_b32_e32 v16, v141
	v_mov_b32_e32 v17, v141

; DI float half_sum(float v) { auto rr = __builtin_amdgcn_permlane32_swap(__float_as_uint(v), __float_as_uint(v), false, false); return __uint_as_float(rr[0]) + __uint_as_float(rr[1]); }
; #define DMA_TILE(Kp, Vp, slot) do { \
;         glds16((Kp) + kofs, (unsigned)__builtin_amdgcn_readfirstlane((int)(lds_base + (unsigned)((slot) * ATT_BUF + w * 1024)))); \
;         glds16((Vp) + vofs, (unsigned)__builtin_amdgcn_readfirstlane((int)(lds_base + (unsigned)((slot) * ATT_BUF + LDS_VT + w * 1024)))); } while (0)
; #define WAIT_VM(n) asm volatile("s_waitcnt vmcnt(" #n ")" ::: "memory")
; #define LBAR() do { asm volatile("s_waitcnt lgkmcnt(0)" ::: "memory"); __builtin_amdgcn_s_barrier(); asm volatile("" ::: "memory"); } while (0)
; #define TILE_SRC(ii, kp, vp) do { const int jn_ = LIST[(ii)]; const bool ns_ = (ii) < nsel; kp = KS + (ns_ ? (size_t)0 : 2 * KV_SLOT) + (size_t)jn_ * 4096; vp = kp + KV_SLOT; } while (0)
; DI void attn_unit(LAS unsigned char* lds, const Args& a, int bg, int qt) {
;     ...
;     for (int i = 0; i < ntile; ++i) {
;         const int j = LIST[i]; const bool is_sel = i < nsel;
;         if (i + 2 < ntile) WAIT_VM(4); else if (i + 1 < ntile) WAIT_VM(2); else WAIT_VM(0);
;         LBAR();
;         if (i + 3 < ntile) { const bf16_t* kp; const bf16_t* vp; TILE_SRC(i + 3, kp, vp); DMA_TILE(kp, vp, (i + 1) & 3); }
;         if (i == nsel) {
;             const float lt = half_sum(l_run); const float gi = GT[512] / lt;
; #pragma unroll
;             for (int r = 0; r < 16; ++r) { oacc[0][r] += gi * o[0][r]; oacc[1][r] += gi * o[1][r]; o[0][r] = 0.f; o[1][r] = 0.f; }
;             m_ref = 0.f; l_run = 0.f;
;         }
.LBB0_786:
	s_waitcnt lgkmcnt(0)
	s_barrier
.LBB0_788:
	s_add_i32 s8, s28, s77
	s_cmp_lg_u32 s8, 3
	s_cbranch_scc1 .LBB0_790
	ds_read_b32 v18, v133 offset:2048
	v_mov_b32_e32 v2, v141
	s_nop 1
	v_permlane32_swap_b32_e32 v141, v2
	v_add_f32_e32 v2, v141, v2
	s_waitcnt lgkmcnt(0)
	v_div_scale_f32 v19, s[8:9], v2, v2, v18
	v_rcp_f32_e32 v20, v19
	v_div_scale_f32 v21, vcc, v18, v2, v18
	v_mov_b32_e32 v51, v3
	v_fma_f32 v22, -v19, v20, 1.0
	v_fmac_f32_e32 v20, v22, v20
	v_mul_f32_e32 v22, v21, v20
	v_fma_f32 v23, -v19, v22, v21
	v_fmac_f32_e32 v22, v23, v20
	v_fma_f32 v19, -v19, v22, v21
	v_div_fmas_f32 v19, v19, v20, v22
	v_div_fixup_f32 v2, v19, v2, v18
	v_mov_b32_e32 v143, 0
	v_pk_fma_f32 v[166:167], v[50:51], v[2:3], v[166:167] op_sel_hi:[1,0,1]
	v_pk_fma_f32 v[164:165], v[4:5], v[2:3], v[164:165] op_sel_hi:[1,0,1]
	v_pk_fma_f32 v[162:163], v[6:7], v[2:3], v[162:163] op_sel_hi:[1,0,1]
	v_pk_fma_f32 v[160:161], v[8:9], v[2:3], v[160:161] op_sel_hi:[1,0,1]
	v_pk_fma_f32 v[158:159], v[10:11], v[2:3], v[158:159] op_sel_hi:[1,0,1]
	v_pk_fma_f32 v[156:157], v[12:13], v[2:3], v[156:157] op_sel_hi:[1,0,1]
	v_pk_fma_f32 v[154:155], v[14:15], v[2:3], v[154:155] op_sel_hi:[1,0,1]
	v_pk_fma_f32 v[168:169], v[48:49], v[2:3], v[168:169] op_sel_hi:[1,0,1]
	v_pk_fma_f32 v[170:171], v[46:47], v[2:3], v[170:171] op_sel_hi:[1,0,1]
	v_pk_fma_f32 v[172:173], v[44:45], v[2:3], v[172:173] op_sel_hi:[1,0,1]
	v_pk_fma_f32 v[174:175], v[42:43], v[2:3], v[174:175] op_sel_hi:[1,0,1]
	v_pk_fma_f32 v[176:177], v[40:41], v[2:3], v[176:177] op_sel_hi:[1,0,1]
	v_pk_fma_f32 v[178:179], v[38:39], v[2:3], v[178:179] op_sel_hi:[1,0,1]
	v_pk_fma_f32 v[180:181], v[36:37], v[2:3], v[180:181] op_sel_hi:[1,0,1]
	v_pk_fma_f32 v[182:183], v[34:35], v[2:3], v[182:183] op_sel_hi:[1,0,1]
	v_pk_fma_f32 v[152:153], v[16:17], v[2:3], v[152:153] op_sel_hi:[1,0,1]
	v_mov_b32_e32 v141, 0
	v_mov_b32_e32 v18, 0
	v_mov_b32_e32 v19, v143
	v_mov_b32_e32 v20, v143
	v_mov_b32_e32 v21, v143
	v_mov_b32_e32 v22, v143
	v_mov_b32_e32 v23, v143
	v_mov_b32_e32 v24, v143
	v_mov_b32_e32 v25, v143
	v_mov_b32_e32 v26, v143
	v_mov_b32_e32 v27, v143
	v_mov_b32_e32 v28, v143
	v_mov_b32_e32 v29, v143
	v_mov_b32_e32 v30, v143
	v_mov_b32_e32 v31, v143
	v_mov_b32_e32 v32, v143
	v_mov_b32_e32 v33, v143
	v_mov_b32_e32 v2, v143
	v_mov_b32_e32 v3, v143
	v_mov_b32_e32 v4, v143
	v_mov_b32_e32 v5, v143
	v_mov_b32_e32 v6, v143
	v_mov_b32_e32 v7, v143
	v_mov_b32_e32 v8, v143
	v_mov_b32_e32 v9, v143
	v_mov_b32_e32 v10, v143
	v_mov_b32_e32 v11, v143
	v_mov_b32_e32 v12, v143
	v_mov_b32_e32 v13, v143
	v_mov_b32_e32 v14, v143
	v_mov_b32_e32 v15, v143
	v_mov_b32_e32 v16, v143
	v_mov_b32_e32 v17, v143

; #define DMA_TILE(Kp, Vp, slot) do { \
;         glds16((Kp) + kofs, (unsigned)__builtin_amdgcn_readfirstlane((int)(lds_base + (unsigned)((slot) * ATT_BUF + w * 1024)))); \
;         glds16((Vp) + vofs, (unsigned)__builtin_amdgcn_readfirstlane((int)(lds_base + (unsigned)((slot) * ATT_BUF + LDS_VT + w * 1024)))); } while (0)
; #define WAIT_VM(n) asm volatile("s_waitcnt vmcnt(" #n ")" ::: "memory")
; #define LBAR() do { asm volatile("s_waitcnt lgkmcnt(0)" ::: "memory"); __builtin_amdgcn_s_barrier(); asm volatile("" ::: "memory"); } while (0)
; #define TILE_SRC(ii, kp, vp) do { const int jn_ = LIST[(ii)]; const bool ns_ = (ii) < nsel; kp = KS + (ns_ ? (size_t)0 : 2 * KV_SLOT) + (size_t)jn_ * 4096; vp = kp + KV_SLOT; } while (0)
; DI void attn_unit(LAS unsigned char* lds, const Args& a, int bg, int qt) {
;     ...
;     if (ntile > 1) { const bf16_t* kp; const bf16_t* vp; TILE_SRC(1, kp, vp); DMA_TILE(kp, vp, 3); }
;     if (ntile > 2) { const bf16_t* kp; const bf16_t* vp; TILE_SRC(2, kp, vp); DMA_TILE(kp, vp, 0); }
;     for (int i = 0; i < ntile; ++i) {
;         const int j = LIST[i]; const bool is_sel = i < nsel;
;         if (i + 2 < ntile) WAIT_VM(4); else if (i + 1 < ntile) WAIT_VM(2); else WAIT_VM(0);
;         LBAR();
;         if (i + 3 < ntile) { const bf16_t* kp; const bf16_t* vp; TILE_SRC(i + 3, kp, vp); DMA_TILE(kp, vp, (i + 1) & 3); }
.LBB0_806:
	s_cmp_le_i32 s77, s18
	s_cbranch_scc1 .Lattn_w2
	s_waitcnt vmcnt(0)
	s_branch .Lattn_w2d
.Lattn_w2:
	s_waitcnt vmcnt(2)
.Lattn_w2d:
	s_barrier
	s_cmp_ge_i32 s77, s18
	s_cbranch_scc1 .Lattn_nodma
	v_mov_b32_e32 v86, s78
	ds_read_b32 v82, v86
	s_cmp_lt_i32 s77, s19
	s_cselect_b32 s8, 0, 0x2000000
	s_add_u32 s8, s54, s8
	s_addc_u32 s9, s55, 0
	s_waitcnt lgkmcnt(0)
	v_ashrrev_i32_e32 v83, 31, v82
	v_lshlrev_b64 v[82:83], 13, v[82:83]
	v_lshl_add_u64 v[82:83], s[8:9], 0, v[82:83]
	s_add_i32 s8, s29, 0xc000
	s_and_b32 s8, s8, 0xc000
	s_add_i32 s8, s8, s75
	v_mov_b32_e32 v151, v101
	v_lshl_add_u64 v[84:85], v[82:83], 0, v[100:101]
	s_add_i32 s9, s8, 0
	s_mov_b32 s10, m0
	s_mov_b32 m0, s9
	s_nop 0
	global_load_lds_dwordx4 v[84:85], off
	s_mov_b32 m0, s10
	v_lshl_add_u64 v[82:83], v[82:83], 0, v[150:151]
	s_addk_i32 s8, 0x2000
	v_lshl_add_u64 v[82:83], v[82:83], 0, s[50:51]
	s_add_i32 s8, s8, 0
	s_mov_b32 s9, m0
	s_mov_b32 m0, s8
	s_nop 0
	global_load_lds_dwordx4 v[82:83], off
	s_mov_b32 m0, s9

; DI void attn_unit(LAS unsigned char* lds, const Args& a, int bg, int qt) {
;     ...
;         attn_tile(kb, kb + LDS_VT, qf, ql, hi, need_mask, col_en, lo_b, hi_b, m_ref, l_run, o, sp);
;     }
.Lattn_exit:
	s_cmp_ge_u32 s98, 0x100
	s_cbranch_scc1 .LBB0_738
	s_barrier
	s_branch .LBB0_738

; #define LAS __attribute__((address_space(3)))
; __global__ void __launch_bounds__(512, 2) mk_fwd(Args args) {
;     extern __shared__ __attribute__((aligned(16))) unsigned char lds_raw[];
;     LAS unsigned char* lds = (LAS unsigned char*)lds_raw;
	.amdhsa_kernel _Z6mk_fwd4Args
		.amdhsa_group_segment_fixed_size 0
		.amdhsa_private_segment_fixed_size 0
		.amdhsa_kernarg_size 464
		.amdhsa_user_sgpr_count 2
		.amdhsa_user_sgpr_dispatch_ptr 0
		.amdhsa_user_sgpr_queue_ptr 0
		.amdhsa_user_sgpr_kernarg_segment_ptr 1
		.amdhsa_user_sgpr_dispatch_id 0
		.amdhsa_user_sgpr_kernarg_preload_length 0
		.amdhsa_user_sgpr_kernarg_preload_offset 0
		.amdhsa_user_sgpr_private_segment_size 0
		.amdhsa_uses_dynamic_stack 0
		.amdhsa_enable_private_segment 0
		.amdhsa_system_sgpr_workgroup_id_x 1
		.amdhsa_system_sgpr_workgroup_id_y 0
		.amdhsa_system_sgpr_workgroup_id_z 0
		.amdhsa_system_sgpr_workgroup_info 0
		.amdhsa_system_vgpr_workitem_id 2
		.amdhsa_next_free_vgpr 256
		.amdhsa_next_free_sgpr 99
		.amdhsa_accum_offset 256
		.amdhsa_reserve_vcc 1
		.amdhsa_float_round_mode_32 0
		.amdhsa_float_round_mode_16_64 0
		.amdhsa_float_denorm_mode_32 3
		.amdhsa_float_denorm_mode_16_64 3
		.amdhsa_dx10_clamp 1
		.amdhsa_ieee_mode 1
		.amdhsa_fp16_overflow 0
		.amdhsa_tg_split 0
		.amdhsa_exception_fp_ieee_invalid_op 0
		.amdhsa_exception_fp_denorm_src 0
		.amdhsa_exception_fp_ieee_div_zero 0
		.amdhsa_exception_fp_ieee_overflow 0
		.amdhsa_exception_fp_ieee_underflow 0
		.amdhsa_exception_fp_ieee_inexact 0
		.amdhsa_exception_int_div_zero 0
	.end_amdhsa_kernel
